# P4 tile stream: K/V LDS-DMA pieces as SGPR base + per-lane byte offset (no address VALU behind the workgroup barrier)
# speedup vs baseline: 1.0156x; 1.0003x over previous
.LBB0_610:
	v_ashrrev_i32_e32 v5, 1, v87
	v_xor_b32_e32 v6, v5, v192
	s_lshl_b32 s0, s24, 10
	s_ashr_i32 s11, s10, 31
	v_lshlrev_b32_e32 v4, 6, v87
	v_lshlrev_b32_e32 v6, 3, v6
	s_add_i32 s46, s0, 0
	s_lshl_b64 s[0:1], s[10:11], 13
	v_and_b32_e32 v3, 7, v192
	v_and_or_b32 v166, v6, 56, v4
	v_lshlrev_b32_e32 v5, 2, v5
	s_add_u32 s20, s6, s0
	v_bitop3_b32 v3, v5, v3, 4 bitop3:0x6c
	s_addc_u32 s21, s7, s1
	v_ashrrev_i32_e32 v167, 31, v166
	v_lshl_or_b32 v168, v3, 3, v4
	s_mov_b32 m0, s46
	v_lshlrev_b32_e32 v166, 1, v166
	global_load_lds_dwordx4 v166, s[20:21]
	s_add_u32 s20, s8, s0
	s_addc_u32 s21, s9, s1
	s_add_i32 m0, s46, 0x2000
	v_lshlrev_b32_e32 v168, 1, v168
	global_load_lds_dwordx4 v168, s[20:21]
	s_cmp_ge_i32 s10, s42
	s_cbranch_scc1 .LBB0_612
	s_add_u32 s0, s0, 0x2000
	s_addc_u32 s1, s1, 0
	s_add_u32 s20, s6, s0
	s_addc_u32 s21, s7, s1
	s_add_i32 m0, s46, 0x4000
	s_nop 0
	global_load_lds_dwordx4 v166, s[20:21]
	s_add_u32 s20, s8, s0
	s_addc_u32 s21, s9, s1
	s_add_i32 m0, s46, 0x6000
	s_nop 0
	global_load_lds_dwordx4 v168, s[20:21]

.LBB0_643:
	s_waitcnt vmcnt(0)
	s_barrier
	v_cmp_le_i32_e32 vcc, s43, v197
	s_cbranch_vccnz .LBB0_648
	s_cmp_eq_u32 s48, 1
	s_cselect_b32 s0, s12, s16
	s_cselect_b32 s1, s13, s17
	s_cselect_b32 s21, s14, s18
	s_cselect_b32 s38, s15, s19
	s_cmp_eq_u32 s48, 0
	s_cselect_b32 s39, s7, s1
	s_cselect_b32 s40, s6, s0
	s_cselect_b32 s76, s9, s38
	s_cselect_b32 s77, s8, s21
	s_cselect_b32 s38, s42, s45
	s_lshl_b32 s0, s49, 15
	s_and_b32 s0, s0, 0x8000
	s_ashr_i32 s21, s20, 31
	s_add_i32 s41, s46, s0
	s_lshl_b64 s[0:1], s[20:21], 13
	s_add_u32 s78, s40, s0
	s_addc_u32 s79, s39, s1
	s_mov_b32 m0, s41
	s_nop 0
	global_load_lds_dwordx4 v166, s[78:79]
	s_add_u32 s78, s77, s0
	s_addc_u32 s79, s76, s1
	s_add_i32 m0, s41, 0x2000
	s_nop 0
	global_load_lds_dwordx4 v168, s[78:79]
	s_cmp_ge_i32 s20, s38
	s_cbranch_scc1 .LBB0_646
	s_add_u32 s0, s0, 0x2000
	s_addc_u32 s1, s1, 0
	s_add_u32 s78, s40, s0
	s_addc_u32 s79, s39, s1
	s_add_i32 m0, s41, 0x4000
	s_nop 0
	global_load_lds_dwordx4 v166, s[78:79]
	s_add_u32 s78, s77, s0
	s_addc_u32 s79, s76, s1
	s_add_i32 m0, s41, 0x6000
	s_nop 0
	global_load_lds_dwordx4 v168, s[78:79]
